# EpiBranch gate/partial-merge tile loads marked non-temporal; weight-convert loop waits only for its prefetched loads (vmcnt(4)) instead of also for the previous tile's stores
# baseline (speedup 1.0000x reference)
.LBB0_192:
	v_lshl_add_u32 v134, s16, 8, v64
	v_lshl_or_b32 v132, s64, 8, v143
	v_lshlrev_b32_e32 v134, 12, v134
	v_lshl_add_u32 v132, v132, 1, v134
	v_readfirstlane_b32 s64, v130
	v_readfirstlane_b32 s65, v131
	s_nop 4
	v_mov_b32_e32 v133, v132
	global_load_dwordx4 v[196:199], v133, s[4:5] nt
	global_load_dwordx4 v[200:203], v133, s[4:5] offset:256 nt
	v_add_u32_e32 v133, 0x10000, v132
	global_load_dwordx4 v[204:207], v133, s[4:5] nt
	global_load_dwordx4 v[208:211], v133, s[4:5] offset:256 nt
	v_add_u32_e32 v133, 0x20000, v132
	global_load_dwordx4 v[212:215], v133, s[4:5] nt
	global_load_dwordx4 v[216:219], v133, s[4:5] offset:256 nt
	v_add_u32_e32 v133, 0x30000, v132
	global_load_dwordx4 v[220:223], v133, s[4:5] nt
	global_load_dwordx4 v[224:227], v133, s[4:5] offset:256 nt
	s_cmp_lg_u64 s[12:13], 0
	s_cbranch_scc0 .Lepb_nom0
	v_mov_b32_e32 v133, v132
	global_load_dwordx4 v[228:231], v133, s[64:65] nt
	global_load_dwordx4 v[232:235], v133, s[64:65] offset:256 nt
	v_add_u32_e32 v133, 0x10000, v132
	global_load_dwordx4 v[236:239], v133, s[64:65] nt
	global_load_dwordx4 v[240:243], v133, s[64:65] offset:256 nt
	v_add_u32_e32 v133, 0x20000, v132
	global_load_dwordx4 v[244:247], v133, s[64:65] nt
	global_load_dwordx4 v[176:179], v133, s[64:65] offset:256 nt
	v_add_u32_e32 v133, 0x30000, v132
	global_load_dwordx4 v[134:137], v133, s[64:65] nt
	global_load_dwordx4 v[138:141], v133, s[64:65] offset:256 nt

.Lepb_na7:
	v_cvt_pk_bf16_f32 v224, v70, v71
	v_cvt_pk_bf16_f32 v225, v72, v73
	v_cvt_pk_bf16_f32 v226, v66, v67
	v_cvt_pk_bf16_f32 v227, v68, v69
	v_add_u32_e32 v133, 0x30000, v132
	global_store_dwordx4 v133, v[224:227], s[8:9] offset:256
	v_add_u32_e32 v133, 0x80000, v132
	global_load_dwordx4 v[196:199], v133, s[4:5] nt
	global_load_dwordx4 v[200:203], v133, s[4:5] offset:256 nt
	v_add_u32_e32 v133, 0x90000, v132
	global_load_dwordx4 v[204:207], v133, s[4:5] nt
	global_load_dwordx4 v[208:211], v133, s[4:5] offset:256 nt
	v_add_u32_e32 v133, 0xa0000, v132
	global_load_dwordx4 v[212:215], v133, s[4:5] nt
	global_load_dwordx4 v[216:219], v133, s[4:5] offset:256 nt
	v_add_u32_e32 v133, 0xb0000, v132
	global_load_dwordx4 v[220:223], v133, s[4:5] nt
	global_load_dwordx4 v[224:227], v133, s[4:5] offset:256 nt
	s_cmp_lg_u64 s[12:13], 0
	s_cbranch_scc0 .Lepb_nom1
	v_add_u32_e32 v133, 0x80000, v132
	global_load_dwordx4 v[228:231], v133, s[64:65] nt
	global_load_dwordx4 v[232:235], v133, s[64:65] offset:256 nt
	v_add_u32_e32 v133, 0x90000, v132
	global_load_dwordx4 v[236:239], v133, s[64:65] nt
	global_load_dwordx4 v[240:243], v133, s[64:65] offset:256 nt
	v_add_u32_e32 v133, 0xa0000, v132
	global_load_dwordx4 v[244:247], v133, s[64:65] nt
	global_load_dwordx4 v[176:179], v133, s[64:65] offset:256 nt
	v_add_u32_e32 v133, 0xb0000, v132
	global_load_dwordx4 v[134:137], v133, s[64:65] nt
	global_load_dwordx4 v[138:141], v133, s[64:65] offset:256 nt

.LBB0_443:
	s_or_b64 exec, exec, s[6:7]
	v_lshlrev_b32_e32 v32, 5, v34
	v_ashrrev_i32_e32 v45, 1, v34
	v_and_b32_e32 v32, 32, v32
	s_movk_i32 s3, 0x104
	v_mad_u32_u24 v34, v32, s3, v45
	s_movk_i32 s3, 0x410
	v_lshl_add_u32 v33, v36, 2, 0
	v_lshl_add_u32 v46, v34, 2, 0
	v_mul_lo_u32 v34, v37, s3
	v_mul_lo_u32 v35, v38, s3
	v_mul_lo_u32 v49, v39, s3
	v_mul_lo_u32 v50, v40, s3
	v_mul_lo_u32 v51, v41, s3
	v_mul_lo_u32 v52, v42, s3
	v_mul_lo_u32 v53, v43, s3
	v_mul_lo_u32 v54, v44, s3
	v_add_u32_e32 v47, v33, v34
	v_add_u32_e32 v48, v33, v35
	v_add_u32_e32 v49, v33, v49
	v_add_u32_e32 v50, v33, v50
	v_add_u32_e32 v51, v33, v51
	v_add_u32_e32 v52, v33, v52
	v_add_u32_e32 v53, v33, v53
	v_add_u32_e32 v54, v33, v54
	v_lshlrev_b32_e32 v32, 1, v32
	s_mov_b32 s10, s34
	s_waitcnt vmcnt(0)
	s_branch .LBB0_446

.LBB0_446:
	s_add_i32 s3, s10, s42
	s_cmpk_gt_i32 s3, 0xa1f
	s_cselect_b64 s[4:5], -1, 0
	s_and_b64 vcc, exec, s[4:5]
	s_waitcnt vmcnt(4)
	ds_write_b128 v47, v[4:7]
	ds_write_b128 v48, v[0:3]
	ds_write_b128 v49, v[8:11]
	ds_write_b128 v50, v[12:15]
	ds_write_b128 v51, v[16:19]
	ds_write_b128 v52, v[20:23]
	ds_write_b128 v53, v[24:27]
	ds_write_b128 v54, v[28:31]
	s_waitcnt lgkmcnt(0)
	s_barrier
	s_cbranch_vccnz .LBB0_445
	s_mul_hi_i32 s6, s3, 0x1948b0fd
	s_lshr_b32 s7, s6, 31
	s_ashr_i32 s6, s6, 8
	s_add_i32 s6, s6, s7
	s_mul_i32 s7, s6, 0xfffff5e0
	s_add_i32 s8, s3, s7
	s_mul_hi_i32 s7, s6, 0xa040000
	s_mul_i32 s6, s6, 0xa040000
	s_add_u32 s6, s0, s6
	s_mul_hi_i32 s9, s8, 0x1948b0fd
	s_addc_u32 s7, s2, s7
	s_lshr_b32 s11, s9, 31
	s_ashr_i32 s9, s9, 3
	s_add_i32 s9, s9, s11
	s_mul_i32 s11, s9, 0x51
	s_sub_i32 s8, s8, s11
	s_lshl_b32 s8, s8, 8
	v_or_b32_e32 v0, s8, v36
	s_cmpk_lt_u32 s8, 0x5000
	s_movk_i32 s8, 0x5020
	v_add_u32_e32 v1, 0xffffe000, v0
	v_cmp_gt_u32_e32 vcc, s8, v0
	v_add_u32_e32 v2, 32, v0
	s_movk_i32 s8, 0x3000
	v_cndmask_b32_e32 v1, -1, v1, vcc
	s_cselect_b64 vcc, -1, 0
	v_cndmask_b32_e32 v1, v1, v2, vcc
	v_cmp_gt_i32_e32 vcc, s8, v0
	v_mov_b32_e32 v2, v65
	v_mov_b32_e32 v3, v65
	v_cndmask_b32_e32 v34, v1, v0, vcc
	v_mov_b32_e32 v0, v65
	v_mov_b32_e32 v1, v65
	v_mov_b64_e32 v[6:7], v[2:3]
	s_lshl_b32 s11, s9, 6
	v_cmp_lt_i32_e32 vcc, -1, v34
	v_mov_b64_e32 v[4:5], v[0:1]
	s_and_saveexec_b64 s[8:9], vcc
	s_cbranch_execz .LBB0_449
	v_add_u32_e32 v6, s11, v37
	v_mov_b64_e32 v[4:5], s[6:7]
	s_mov_b32 s12, 0x14080
	v_mad_i64_i32 v[4:5], s[12:13], v6, s12, v[4:5]
	v_mov_b32_e32 v35, v65
	v_lshl_add_u64 v[4:5], v[34:35], 2, v[4:5]
	global_load_dwordx4 v[4:7], v[4:5], off nt
